# attention: waves 0-3 of a unit skip the last key-tile step and the drain (both fully masked for their rows: they only add zeros)
# speedup vs baseline: 1.0041x; 1.0041x over previous
.LBB0_467:
	s_cmp_gt_u32 s86, 3
	s_cbranch_scc1 .Lfin_go
	v_cmp_gt_u32_e32 vcc, 32, v234
	v_mov_b32_e32 v98, v247
	v_mov_b32_e32 v66, v247
	s_nop 1
	v_permlane32_swap_b32_e32 v98, v66
	s_and_saveexec_b64 s[4:5], vcc
	s_cbranch_execz .LBB0_386
	v_add_f32_e32 v1, v98, v66
	ds_write_b32 v240, v1 offset:128
	s_branch .LBB0_386
